# memory cross-attention: second loop copy without running row max or per-tile rescale, taken when max|q gain|*max|k gain| < 3 proves the scores bounded
# baseline (speedup 1.0000x reference)
.Lxf_loop:
	v_lshl_add_u64 v[80:81], s[78:79], 0, v[146:147]
	v_add_co_u32_e32 v94, vcc, s40, v80
	v_lshl_add_u64 v[76:77], s[78:79], 0, v[144:145]
	s_nop 0
	v_addc_co_u32_e32 v95, vcc, 0, v81, vcc
	v_add_co_u32_e32 v90, vcc, s40, v76
	v_lshl_add_u64 v[72:73], s[78:79], 0, v[142:143]
	s_nop 0
	v_addc_co_u32_e32 v91, vcc, 0, v77, vcc
	v_add_co_u32_e32 v86, vcc, s40, v72
	v_lshl_add_u64 v[68:69], s[78:79], 0, v[140:141]
	s_nop 0
	v_addc_co_u32_e32 v87, vcc, 0, v73, vcc
	v_add_co_u32_e32 v82, vcc, s40, v68
	v_lshl_add_u64 v[66:67], s[78:79], 0, v[154:155]
	v_lshl_add_u64 v[70:71], s[78:79], 0, v[152:153]
	v_lshl_add_u64 v[74:75], s[78:79], 0, v[150:151]
	v_lshl_add_u64 v[78:79], s[78:79], 0, v[148:149]
	v_addc_co_u32_e32 v83, vcc, 0, v69, vcc
	global_load_dwordx4 v[66:69], v[66:67], off
	s_nop 0
	global_load_dwordx4 v[70:73], v[70:71], off
	s_nop 0
	global_load_dwordx4 v[74:77], v[74:75], off
	s_nop 0
	global_load_dwordx4 v[78:81], v[78:79], off
	s_nop 0
	global_load_dwordx4 v[82:85], v[82:83], off
	s_nop 0
	global_load_dwordx4 v[86:89], v[86:87], off
	s_nop 0
	global_load_dwordx4 v[90:93], v[90:91], off
	s_nop 0
	global_load_dwordx4 v[94:97], v[94:95], off
	s_bitcmp1_b32 s8, 0
	s_cselect_b32 s9, 0x8800, 0
	s_add_i32 s9, s13, s9
	v_add3_u32 v130, s9, v161, v162
	v_add3_u32 v131, s9, v163, v164
	v_add3_u32 v132, s9, v165, v166
	v_add3_u32 v133, s9, v167, v168
	v_add_u32_e32 v176, s9, v160
	v_add3_u32 v177, s9, v134, v173
	v_add3_u32 v179, v176, v169, s39
	v_add3_u32 v180, v176, v170, s39
	v_add3_u32 v181, v176, v171, s39
	v_add3_u32 v176, v176, v172, s39
	s_add_i32 s8, s8, 1
	v_lshl_add_u64 v[140:141], v[140:141], 0, s[0:1]
	v_lshl_add_u64 v[142:143], v[142:143], 0, s[0:1]
	v_lshl_add_u64 v[144:145], v[144:145], 0, s[0:1]
	v_lshl_add_u64 v[146:147], v[146:147], 0, s[0:1]
	v_lshl_add_u64 v[148:149], v[148:149], 0, s[6:7]
	v_lshl_add_u64 v[150:151], v[150:151], 0, s[6:7]
	v_lshl_add_u64 v[152:153], v[152:153], 0, s[6:7]
	v_lshl_add_u64 v[154:155], v[154:155], 0, s[6:7]
	s_cmp_lg_u32 s8, 4
	s_waitcnt vmcnt(7)
	ds_write_b128 v130, v[66:69]
	s_waitcnt vmcnt(6)
	ds_write_b128 v131, v[70:73]
	s_waitcnt vmcnt(5)
	ds_write_b128 v132, v[74:77]
	s_waitcnt vmcnt(4)
	ds_write_b128 v133, v[78:81]
	s_waitcnt vmcnt(3)
	ds_write2_b64 v179, v[82:83], v[84:85] offset1:1
	s_waitcnt vmcnt(2)
	ds_write2_b64 v180, v[86:87], v[88:89] offset1:1
	s_waitcnt vmcnt(1)
	ds_write2_b64 v181, v[90:91], v[92:93] offset1:1
	s_waitcnt vmcnt(0)
	ds_write2_b64 v176, v[94:95], v[96:97] offset1:1
	s_waitcnt lgkmcnt(0)
	s_barrier
	ds_read_b128 v[66:69], v177
	ds_read_b128 v[130:133], v177 offset:32
	s_waitcnt lgkmcnt(1)
	v_mfma_f32_32x32x16_bf16 v[82:97], v[66:69], v[98:101], 0
	ds_read_b128 v[66:69], v177 offset:8704
	ds_read_b128 v[180:183], v177 offset:8736
	v_mov_b32_e32 v176, v178
	s_waitcnt lgkmcnt(1)
	v_mfma_f32_32x32x16_bf16 v[66:81], v[66:69], v[98:101], 0
	v_mfma_f32_32x32x16_bf16 v[82:97], v[130:133], v[102:105], v[82:97]
	s_waitcnt lgkmcnt(0)
	v_mfma_f32_32x32x16_bf16 v[66:81], v[180:183], v[102:105], v[66:81]
	ds_read_b128 v[130:133], v177 offset:64
	ds_read_b128 v[180:183], v177 offset:96
	s_waitcnt lgkmcnt(1)
	v_mfma_f32_32x32x16_bf16 v[82:97], v[130:133], v[106:109], v[82:97]
	ds_read_b128 v[130:133], v177 offset:8768
	ds_read_b128 v[184:187], v177 offset:8800
	s_waitcnt lgkmcnt(1)
	v_mfma_f32_32x32x16_bf16 v[66:81], v[130:133], v[106:109], v[66:81]
	v_mfma_f32_32x32x16_bf16 v[82:97], v[180:183], v[110:113], v[82:97]
	ds_read_b128 v[130:133], v177 offset:128
	ds_read_b128 v[180:183], v177 offset:160
	s_waitcnt lgkmcnt(2)
	v_mfma_f32_32x32x16_bf16 v[66:81], v[184:187], v[110:113], v[66:81]
	s_waitcnt lgkmcnt(1)
	v_mfma_f32_32x32x16_bf16 v[82:97], v[130:133], v[114:117], v[82:97]
	ds_read_b128 v[184:187], v177 offset:8832
	ds_read_b128 v[130:133], v177 offset:8864
	s_waitcnt lgkmcnt(1)
	v_mfma_f32_32x32x16_bf16 v[66:81], v[184:187], v[114:117], v[66:81]
	v_mfma_f32_32x32x16_bf16 v[82:97], v[180:183], v[118:121], v[82:97]
	s_waitcnt lgkmcnt(0)
	v_mfma_f32_32x32x16_bf16 v[66:81], v[130:133], v[118:121], v[66:81]
	ds_read_b128 v[130:133], v177 offset:192
	ds_read_b128 v[178:181], v177 offset:224
	s_waitcnt lgkmcnt(1)
	v_mfma_f32_32x32x16_bf16 v[82:97], v[130:133], v[122:125], v[82:97]
	ds_read_b128 v[130:133], v177 offset:8896
	ds_read_b128 v[182:185], v177 offset:8928
	s_waitcnt lgkmcnt(1)
	v_mfma_f32_32x32x16_bf16 v[66:81], v[130:133], v[122:125], v[66:81]
	v_add3_u32 v130, s9, v138, v174
	v_add_u32_e32 v177, 0x4000, v130
	v_add_u32_e32 v203, 0x5000, v130
	v_add_u32_e32 v204, 0x6000, v130
	v_add_u32_e32 v205, 0x7000, v130
	v_mfma_f32_32x32x16_bf16 v[82:97], v[178:181], v[126:129], v[82:97]
	ds_read2_b64 v[130:133], v177 offset0:128 offset1:130
	ds_read2_b64 v[178:181], v177 offset0:132 offset1:134
	ds_read2_b64 v[186:189], v203 offset0:160 offset1:162
	ds_read2_b64 v[190:193], v204 offset0:192 offset1:194
	ds_read2_b64 v[194:197], v205 offset0:224 offset1:226
	ds_read2_b64 v[198:201], v203 offset0:164 offset1:166
	s_waitcnt lgkmcnt(6)
	v_mfma_f32_32x32x16_bf16 v[66:81], v[182:185], v[126:129], v[66:81]
	s_nop 3
	s_waitcnt lgkmcnt(0)
	v_exp_f32_e32 v207, v82
	v_exp_f32_e32 v208, v83
	v_exp_f32_e32 v209, v84
	v_exp_f32_e32 v210, v85
	v_exp_f32_e32 v211, v86
	v_exp_f32_e32 v212, v87
	v_exp_f32_e32 v213, v88
	v_exp_f32_e32 v214, v89
	v_cvt_pk_bf16_f32 v82, v207, v208
	v_cvt_pk_bf16_f32 v83, v209, v210
	v_cvt_pk_bf16_f32 v84, v211, v212
	v_cvt_pk_bf16_f32 v85, v213, v214
	s_nop 1
	v_mfma_f32_32x32x16_bf16 v[50:65], v[130:133], v[82:85], v[50:65]
	v_mfma_f32_32x32x16_bf16 v[34:49], v[186:189], v[82:85], v[34:49]
	v_mfma_f32_32x32x16_bf16 v[18:33], v[190:193], v[82:85], v[18:33]
	v_exp_f32_e32 v215, v90
	v_exp_f32_e32 v216, v91
	v_exp_f32_e32 v217, v92
	v_exp_f32_e32 v218, v93
	v_exp_f32_e32 v219, v94
	v_mfma_f32_32x32x16_bf16 v[2:17], v[194:197], v[82:85], v[2:17]
	v_exp_f32_e32 v194, v95
	v_exp_f32_e32 v195, v96
	v_exp_f32_e32 v196, v97
	v_cvt_pk_bf16_f32 v82, v215, v216
	v_cvt_pk_bf16_f32 v83, v217, v218
	v_cvt_pk_bf16_f32 v84, v219, v194
	v_cvt_pk_bf16_f32 v85, v195, v196
	s_nop 1
	v_mfma_f32_32x32x16_bf16 v[50:65], v[178:181], v[82:85], v[50:65]
	ds_read2_b64 v[86:89], v204 offset0:196 offset1:198
	ds_read2_b64 v[90:93], v205 offset0:228 offset1:230
	ds_read2_b64 v[94:97], v177 offset0:136 offset1:138
	ds_read2_b64 v[130:133], v203 offset0:168 offset1:170
	ds_read2_b64 v[178:181], v204 offset0:200 offset1:202
	ds_read2_b64 v[182:185], v205 offset0:232 offset1:234
	ds_read2_b64 v[186:189], v177 offset0:140 offset1:142
	v_exp_f32_e32 v177, v70
	v_mfma_f32_32x32x16_bf16 v[34:49], v[198:201], v[82:85], v[34:49]
	ds_read2_b64 v[190:193], v203 offset0:172 offset1:174
	s_waitcnt lgkmcnt(7)
	v_mfma_f32_32x32x16_bf16 v[18:33], v[86:89], v[82:85], v[18:33]
	v_exp_f32_e32 v86, v66
	v_exp_f32_e32 v87, v67
	v_exp_f32_e32 v88, v68
	v_exp_f32_e32 v89, v69
	v_cvt_pk_bf16_f32 v66, v86, v87
	s_waitcnt lgkmcnt(6)
	v_mfma_f32_32x32x16_bf16 v[2:17], v[90:93], v[82:85], v[2:17]
	v_exp_f32_e32 v90, v71
	v_exp_f32_e32 v91, v72
	v_exp_f32_e32 v92, v73
	v_cvt_pk_bf16_f32 v67, v88, v89
	v_cvt_pk_bf16_f32 v68, v177, v90
	ds_read2_b64 v[70:73], v204 offset0:204 offset1:206
	ds_read2_b64 v[82:85], v205 offset0:236 offset1:238
	v_cvt_pk_bf16_f32 v69, v91, v92
	v_exp_f32_e32 v93, v74
	v_exp_f32_e32 v78, v78
	s_waitcnt lgkmcnt(7)
	v_mfma_f32_32x32x16_bf16 v[50:65], v[94:97], v[66:69], v[50:65]
	v_add_f32_e32 v97, 0, v207
	v_exp_f32_e32 v94, v75
	v_exp_f32_e32 v95, v76
	v_exp_f32_e32 v96, v77
	v_exp_f32_e32 v79, v79
	v_exp_f32_e32 v80, v80
	v_exp_f32_e32 v81, v81
	s_waitcnt lgkmcnt(6)
	v_mfma_f32_32x32x16_bf16 v[34:49], v[130:133], v[66:69], v[34:49]
	v_cvt_pk_bf16_f32 v74, v93, v94
	v_cvt_pk_bf16_f32 v75, v95, v96
	v_cvt_pk_bf16_f32 v76, v78, v79
	v_cvt_pk_bf16_f32 v77, v80, v81
	s_waitcnt lgkmcnt(5)
	v_mfma_f32_32x32x16_bf16 v[18:33], v[178:181], v[66:69], v[18:33]
	s_waitcnt lgkmcnt(4)
	v_mfma_f32_32x32x16_bf16 v[2:17], v[182:185], v[66:69], v[2:17]
	v_add_f32_e32 v66, v208, v97
	v_add_f32_e32 v66, v209, v66
	v_add_f32_e32 v66, v210, v66
	v_add_f32_e32 v66, v211, v66
	v_add_f32_e32 v66, v212, v66
	v_add_f32_e32 v66, v213, v66
	v_add_f32_e32 v66, v214, v66
	v_add_f32_e32 v66, v215, v66
	v_add_f32_e32 v66, v216, v66
	v_add_f32_e32 v66, v217, v66
	v_add_f32_e32 v66, v218, v66
	v_add_f32_e32 v66, v219, v66
	v_add_f32_e32 v66, v194, v66
	v_add_f32_e32 v66, v195, v66
	v_add_f32_e32 v66, v196, v66
	v_add_f32_e32 v66, v86, v66
	v_add_f32_e32 v66, v87, v66
	v_add_f32_e32 v66, v88, v66
	v_add_f32_e32 v66, v89, v66
	v_add_f32_e32 v66, v177, v66
	v_add_f32_e32 v66, v90, v66
	v_add_f32_e32 v66, v91, v66
	v_add_f32_e32 v66, v92, v66
	v_add_f32_e32 v66, v93, v66
	s_waitcnt lgkmcnt(3)
	v_mfma_f32_32x32x16_bf16 v[50:65], v[186:189], v[74:77], v[50:65]
	v_add_f32_e32 v66, v94, v66
	v_add_f32_e32 v66, v95, v66
	v_add_f32_e32 v66, v96, v66
	v_add_f32_e32 v66, v78, v66
	v_add_f32_e32 v66, v79, v66
	v_add_f32_e32 v66, v80, v66
	v_add_f32_e32 v178, v81, v66
	s_waitcnt lgkmcnt(2)
	v_mfma_f32_32x32x16_bf16 v[34:49], v[190:193], v[74:77], v[34:49]
	v_add_f32_e32 v178, v176, v178
	s_waitcnt lgkmcnt(1)
	v_mfma_f32_32x32x16_bf16 v[18:33], v[70:73], v[74:77], v[18:33]
	s_waitcnt lgkmcnt(0)
	v_mfma_f32_32x32x16_bf16 v[2:17], v[82:85], v[74:77], v[2:17]
	s_cbranch_scc1 .Lxf_loop
	s_branch .Lxa_join
.LBB0_828:
	s_ashr_i32 s0, s40, 8
	s_add_i32 s12, s0, s83
	s_cmpk_gt_i32 s12, 0x3ff
	s_barrier
	s_cbranch_scc1 .LBB0_833
	s_mul_i32 s0, s0, 0x12600
	v_mbcnt_hi_u32_b32 v157, -1, v254
	s_add_i32 s13, s0, 0
	s_lshr_b32 s0, s40, 8
	v_and_b32_e32 v2, 64, v157
	v_and_b32_e32 v1, 0xff, v0
	s_add_i32 s14, s83, s0
	s_movk_i32 s15, 0xffe0
	v_mov_b32_e32 v135, 0
	v_mov_b32_e32 v156, 0x358637bd
	s_mov_b32 s34, 0x800000
	s_movk_i32 s35, 0x110
	s_movk_i32 s38, 0x88
	s_movk_i32 s39, 0x4400
	s_mov_b32 s40, 0x23d0000
	s_mov_b64 s[0:1], 0x80
	s_mov_b64 s[6:7], 0x10000
	v_xor_b32_e32 v158, 32, v157
	v_add_u32_e32 v159, 64, v2
	v_readlane_b32 s98, v255, 28
	v_readlane_b32 s99, v255, 29
	v_readlane_b32 s100, v255, 30
	v_readlane_b32 s101, v255, 31
	v_mbcnt_lo_u32_b32 v236, -1, 0
	v_mbcnt_hi_u32_b32 v236, -1, v236
	v_lshlrev_b32_e32 v236, 2, v236
	s_nop 4
	global_load_dword v237, v236, s[98:99]
	global_load_dword v238, v236, s[98:99] offset:256
	global_load_dword v240, v236, s[100:101]
	global_load_dword v241, v236, s[100:101] offset:256
	s_waitcnt vmcnt(0)
	v_max_f32_e64 v237, |v237|, |v238|
	v_max_f32_e64 v240, |v240|, |v241|
	v_xor_b32_e32 v238, 4, v236
	ds_bpermute_b32 v241, v238, v237
	ds_bpermute_b32 v242, v238, v240
	s_waitcnt lgkmcnt(0)
	v_max_f32_e32 v237, v237, v241
	v_max_f32_e32 v240, v240, v242
	v_xor_b32_e32 v238, 8, v236
	ds_bpermute_b32 v241, v238, v237
	ds_bpermute_b32 v242, v238, v240
	s_waitcnt lgkmcnt(0)
	v_max_f32_e32 v237, v237, v241
	v_max_f32_e32 v240, v240, v242
	v_xor_b32_e32 v238, 16, v236
	ds_bpermute_b32 v241, v238, v237
	ds_bpermute_b32 v242, v238, v240
	s_waitcnt lgkmcnt(0)
	v_max_f32_e32 v237, v237, v241
	v_max_f32_e32 v240, v240, v242
	v_xor_b32_e32 v238, 32, v236
	ds_bpermute_b32 v241, v238, v237
	ds_bpermute_b32 v242, v238, v240
	s_waitcnt lgkmcnt(0)
	v_max_f32_e32 v237, v237, v241
	v_max_f32_e32 v240, v240, v242
	v_xor_b32_e32 v238, 64, v236
	ds_bpermute_b32 v241, v238, v237
	ds_bpermute_b32 v242, v238, v240
	s_waitcnt lgkmcnt(0)
	v_max_f32_e32 v237, v237, v241
	v_max_f32_e32 v240, v240, v242
	v_xor_b32_e32 v238, 128, v236
	ds_bpermute_b32 v241, v238, v237
	ds_bpermute_b32 v242, v238, v240
	s_waitcnt lgkmcnt(0)
	v_max_f32_e32 v237, v237, v241
	v_max_f32_e32 v240, v240, v242
	v_mul_f32_e32 v237, v237, v240
	v_cmp_gt_f32_e32 vcc, 0x40400000, v237
	s_nop 3
	s_cmp_lg_u64 vcc, 0
	s_cselect_b32 s98, 1, 0
.LBB0_830:
	s_lshl_b32 s9, s12, 5
	s_and_b32 s8, s9, 0xffffff80
	s_addk_i32 s9, 0xc000
	s_and_b32 s42, s14, 3
	s_lshr_b32 s9, s9, 12
	s_lshl_b32 s41, s42, 8
	s_and_b32 s11, s12, 3
	s_ashr_i32 s10, s12, 8
	s_add_i32 s9, s9, 2
	s_cmpk_lt_i32 s8, 0x4000
	s_cselect_b32 s10, s10, s9
	s_ashr_i32 s9, s8, 31
	s_lshl_b64 s[8:9], s[8:9], 10
	v_mov_b32_e32 v50, v1
	s_add_u32 s8, s30, s8
	s_addc_u32 s9, s31, s9
	v_ashrrev_i32_e32 v2, 1, v50
	s_lshl_b32 s11, s11, 8
	v_bfi_b32 v2, s15, v2, v50
	s_add_u32 s8, s8, s11
	v_ashrrev_i32_e32 v3, 31, v2
	s_addc_u32 s9, s9, 0
	v_bfe_u32 v51, v50, 5, 1
	v_lshlrev_b64 v[2:3], 10, v[2:3]
	v_lshl_add_u64 v[136:137], s[8:9], 0, v[2:3]
	v_lshlrev_b32_e32 v134, 4, v51
	v_lshl_add_u64 v[18:19], v[136:137], 0, v[134:135]
	s_barrier
	global_load_dwordx4 v[26:29], v[18:19], off offset:224
	global_load_dwordx4 v[34:37], v[18:19], off offset:192
	global_load_dwordx4 v[42:45], v[18:19], off offset:160
	global_load_dwordx4 v[52:55], v[18:19], off offset:128
	v_cmp_lt_i32_e32 vcc, v158, v159
	v_readlane_b32 s44, v255, 18
	v_lshlrev_b32_e32 v144, 5, v51
	v_cndmask_b32_e32 v2, v157, v158, vcc
	v_readlane_b32 s54, v255, 28
	v_readlane_b32 s55, v255, 29
	v_lshlrev_b32_e32 v139, 2, v2
	s_nop 3
	global_load_dwordx4 v[2:5], v144, s[54:55] offset:336
	global_load_dwordx4 v[6:9], v144, s[54:55] offset:320
	global_load_dwordx4 v[10:13], v144, s[54:55] offset:272
	global_load_dwordx4 v[14:17], v144, s[54:55] offset:256
	global_load_dwordx4 v[56:59], v[18:19], off
	global_load_dwordx4 v[60:63], v[18:19], off offset:32
	global_load_dwordx4 v[64:67], v[18:19], off offset:64
	global_load_dwordx4 v[68:71], v[18:19], off offset:96
	v_lshlrev_b32_e32 v138, 3, v51
	s_ashr_i32 s11, s10, 31
	s_lshl_b64 s[8:9], s[10:11], 18
	s_lshl_b32 s10, s10, 2
	s_or_b32 s10, s10, s42
	s_ashr_i32 s11, s10, 31
	s_lshl_b64 s[10:11], s[10:11], 16
	s_add_u32 s8, s8, 0x2250000
	s_addc_u32 s9, s9, 0
	v_mov_b32_e32 v175, 0xff800000
	v_mov_b32_e32 v178, 0
	v_readlane_b32 s45, v255, 19
	v_readlane_b32 s46, v255, 20
	v_readlane_b32 s47, v255, 21
	v_readlane_b32 s48, v255, 22
	v_readlane_b32 s49, v255, 23
	v_readlane_b32 s50, v255, 24
	v_readlane_b32 s51, v255, 25
	v_readlane_b32 s52, v255, 26
	v_readlane_b32 s53, v255, 27
	v_readlane_b32 s56, v255, 30
	v_readlane_b32 s57, v255, 31
	v_readlane_b32 s58, v255, 32
	v_readlane_b32 s59, v255, 33
	s_waitcnt vmcnt(11)
	v_and_b32_e32 v25, 0xffff0000, v26
	s_waitcnt vmcnt(10)
	v_and_b32_e32 v33, 0xffff0000, v34
	v_lshlrev_b32_e32 v24, 16, v26
	v_lshlrev_b32_e32 v32, 16, v34
	v_mov_b32_e32 v82, v33
	v_mov_b32_e32 v83, v25
	v_lshlrev_b32_e32 v22, 16, v27
	v_lshlrev_b32_e32 v30, 16, v35
	v_mov_b32_e32 v80, v32
	v_mov_b32_e32 v81, v24
	v_pk_mul_f32 v[82:83], v[82:83], v[82:83]
	v_and_b32_e32 v23, 0xffff0000, v27
	v_and_b32_e32 v31, 0xffff0000, v35
	v_mov_b32_e32 v76, v30
	v_mov_b32_e32 v77, v22
	v_pk_fma_f32 v[80:81], v[80:81], v[80:81], v[82:83]
	v_lshlrev_b32_e32 v20, 16, v28
	v_and_b32_e32 v21, 0xffff0000, v28
	v_lshlrev_b32_e32 v28, 16, v36
	v_mov_b32_e32 v78, v31
	v_mov_b32_e32 v79, v23
	v_pk_fma_f32 v[76:77], v[76:77], v[76:77], v[80:81]
	v_lshlrev_b32_e32 v18, 16, v29
	v_and_b32_e32 v19, 0xffff0000, v29
	v_and_b32_e32 v29, 0xffff0000, v36
	v_mov_b32_e32 v72, v28
	v_mov_b32_e32 v73, v20
	v_pk_fma_f32 v[76:77], v[78:79], v[78:79], v[76:77]
	v_lshlrev_b32_e32 v26, 16, v37
	v_mov_b32_e32 v74, v29
	v_mov_b32_e32 v75, v21
	v_pk_fma_f32 v[72:73], v[72:73], v[72:73], v[76:77]
	v_and_b32_e32 v27, 0xffff0000, v37
	v_mov_b32_e32 v48, v26
	v_mov_b32_e32 v49, v18
	v_pk_fma_f32 v[72:73], v[74:75], v[74:75], v[72:73]
	s_waitcnt vmcnt(9)
	v_lshlrev_b32_e32 v34, 16, v45
	v_and_b32_e32 v35, 0xffff0000, v45
	v_lshlrev_b32_e32 v36, 16, v44
	v_and_b32_e32 v37, 0xffff0000, v44
	v_lshlrev_b32_e32 v38, 16, v43
	v_and_b32_e32 v39, 0xffff0000, v43
	v_lshlrev_b32_e32 v40, 16, v42
	v_and_b32_e32 v41, 0xffff0000, v42
	s_waitcnt vmcnt(8)
	v_lshlrev_b32_e32 v42, 16, v55
	v_and_b32_e32 v43, 0xffff0000, v55
	v_lshlrev_b32_e32 v44, 16, v54
	v_and_b32_e32 v45, 0xffff0000, v54
	v_mov_b32_e32 v54, v27
	v_mov_b32_e32 v55, v19
	v_pk_fma_f32 v[48:49], v[48:49], v[48:49], v[72:73]
	v_mov_b32_e32 v83, v41
	v_pk_fma_f32 v[92:93], v[54:55], v[54:55], v[48:49]
	v_and_b32_e32 v49, 0xffff0000, v52
	v_lshlrev_b32_e32 v48, 16, v52
	v_mov_b32_e32 v82, v49
	v_lshlrev_b32_e32 v46, 16, v53
	v_mov_b32_e32 v80, v48
	v_mov_b32_e32 v81, v40
	v_pk_mul_f32 v[82:83], v[82:83], v[82:83]
	v_and_b32_e32 v47, 0xffff0000, v53
	v_mov_b32_e32 v76, v46
	v_mov_b32_e32 v77, v38
	v_pk_fma_f32 v[80:81], v[80:81], v[80:81], v[82:83]
	v_mov_b32_e32 v78, v47
	v_mov_b32_e32 v79, v39
	v_pk_fma_f32 v[76:77], v[76:77], v[76:77], v[80:81]
	v_mov_b32_e32 v72, v44
	v_mov_b32_e32 v73, v36
	v_pk_fma_f32 v[76:77], v[78:79], v[78:79], v[76:77]
	v_mov_b32_e32 v74, v45
	v_mov_b32_e32 v75, v37
	v_pk_fma_f32 v[72:73], v[72:73], v[72:73], v[76:77]
	v_mov_b32_e32 v52, v42
	v_mov_b32_e32 v53, v34
	v_pk_fma_f32 v[72:73], v[74:75], v[74:75], v[72:73]
	v_mov_b32_e32 v54, v43
	v_mov_b32_e32 v55, v35
	v_pk_fma_f32 v[52:53], v[52:53], v[52:53], v[72:73]
	s_waitcnt vmcnt(0)
	v_lshlrev_b32_e32 v96, 16, v71
	v_pk_fma_f32 v[94:95], v[54:55], v[54:55], v[52:53]
	v_and_b32_e32 v97, 0xffff0000, v71
	global_load_dwordx4 v[52:55], v144, s[54:55] offset:208
	global_load_dwordx4 v[72:75], v144, s[54:55] offset:192
	v_lshlrev_b32_e32 v112, 16, v70
	v_and_b32_e32 v113, 0xffff0000, v70
	v_lshlrev_b32_e32 v114, 16, v69
	v_and_b32_e32 v115, 0xffff0000, v69
	v_lshlrev_b32_e32 v110, 16, v68
	v_and_b32_e32 v111, 0xffff0000, v68
	v_lshlrev_b32_e32 v116, 16, v67
	v_and_b32_e32 v117, 0xffff0000, v67
	global_load_dwordx4 v[68:71], v144, s[54:55] offset:144
	global_load_dwordx4 v[76:79], v144, s[54:55] offset:128
	v_lshlrev_b32_e32 v108, 16, v66
	v_and_b32_e32 v109, 0xffff0000, v66
	v_lshlrev_b32_e32 v118, 16, v65
	v_and_b32_e32 v119, 0xffff0000, v65
	v_lshlrev_b32_e32 v106, 16, v64
	v_and_b32_e32 v107, 0xffff0000, v64
	global_load_dwordx4 v[64:67], v144, s[54:55] offset:16
	global_load_dwordx4 v[80:83], v144, s[54:55]
	v_mov_b32_e32 v104, v107
	v_mov_b32_e32 v105, v111
	v_mov_b32_e32 v102, v106
	v_mov_b32_e32 v103, v110
	v_pk_mul_f32 v[104:105], v[104:105], v[104:105]
	v_mov_b32_e32 v88, v118
	v_mov_b32_e32 v89, v114
	v_pk_fma_f32 v[102:103], v[102:103], v[102:103], v[104:105]
	v_mov_b32_e32 v90, v119
	v_mov_b32_e32 v91, v115
	v_pk_fma_f32 v[88:89], v[88:89], v[88:89], v[102:103]
	v_mov_b32_e32 v84, v108
	v_mov_b32_e32 v85, v112
	v_pk_fma_f32 v[88:89], v[90:91], v[90:91], v[88:89]
	v_mov_b32_e32 v86, v109
	v_mov_b32_e32 v87, v113
	v_pk_fma_f32 v[84:85], v[84:85], v[84:85], v[88:89]
	v_mov_b32_e32 v98, v116
	v_pk_fma_f32 v[102:103], v[86:87], v[86:87], v[84:85]
	global_load_dwordx4 v[84:87], v144, s[54:55] offset:80
	global_load_dwordx4 v[88:91], v144, s[54:55] offset:64
	v_mov_b32_e32 v99, v96
	v_pk_fma_f32 v[98:99], v[98:99], v[98:99], v[102:103]
	v_and_b32_e32 v103, 0xffff0000, v60
	v_and_b32_e32 v133, 0xffff0000, v56
	v_lshlrev_b32_e32 v102, 16, v60
	v_lshlrev_b32_e32 v132, 16, v56
	v_mov_b32_e32 v142, v133
	v_mov_b32_e32 v143, v103
	v_lshlrev_b32_e32 v122, 16, v61
	v_lshlrev_b32_e32 v130, 16, v57
	v_mov_b32_e32 v140, v132
	v_mov_b32_e32 v141, v102
	v_pk_mul_f32 v[142:143], v[142:143], v[142:143]
	v_mov_b32_e32 v100, v117
	v_mov_b32_e32 v101, v97
	v_and_b32_e32 v123, 0xffff0000, v61
	v_and_b32_e32 v131, 0xffff0000, v57
	v_mov_b32_e32 v126, v130
	v_mov_b32_e32 v127, v122
	v_pk_fma_f32 v[140:141], v[140:141], v[140:141], v[142:143]
	v_pk_fma_f32 v[98:99], v[100:101], v[100:101], v[98:99]
	v_lshlrev_b32_e32 v104, 16, v62
	v_lshlrev_b32_e32 v100, 16, v58
	v_mov_b32_e32 v128, v131
	v_mov_b32_e32 v129, v123
	v_pk_fma_f32 v[126:127], v[126:127], v[126:127], v[140:141]
	v_and_b32_e32 v105, 0xffff0000, v62
	v_and_b32_e32 v101, 0xffff0000, v58
	v_mov_b32_e32 v60, v100
	v_mov_b32_e32 v61, v104
	v_pk_fma_f32 v[126:127], v[128:129], v[128:129], v[126:127]
	v_lshlrev_b32_e32 v120, 16, v63
	v_and_b32_e32 v121, 0xffff0000, v63
	v_lshlrev_b32_e32 v124, 16, v59
	v_mov_b32_e32 v62, v101
	v_mov_b32_e32 v63, v105
	v_pk_fma_f32 v[60:61], v[60:61], v[60:61], v[126:127]
	v_and_b32_e32 v125, 0xffff0000, v59
	v_mov_b32_e32 v56, v124
	v_mov_b32_e32 v57, v120
	v_pk_fma_f32 v[60:61], v[62:63], v[62:63], v[60:61]
	v_mov_b32_e32 v58, v125
	v_mov_b32_e32 v59, v121
	v_pk_fma_f32 v[56:57], v[56:57], v[56:57], v[60:61]
	v_and_b32_e32 v141, 31, v50
	v_pk_fma_f32 v[56:57], v[58:59], v[58:59], v[56:57]
	v_mul_u32_u24_e32 v173, 0x110, v141
	v_add_f32_e32 v56, v56, v57
	v_add_f32_e32 v56, v56, v98
	v_add_f32_e32 v56, v56, v99
	v_add_f32_e32 v56, v56, v94
	v_add_f32_e32 v56, v56, v95
	v_add_f32_e32 v56, v56, v92
	v_add_f32_e32 v92, v56, v93
	ds_bpermute_b32 v93, v139, v92
	global_load_dwordx4 v[56:59], v144, s[54:55] offset:400
	global_load_dwordx4 v[60:63], v144, s[54:55] offset:384
	v_mul_u32_u24_e32 v174, 0x88, v141
	s_waitcnt lgkmcnt(0)
	v_add_f32_e32 v92, v92, v93
	v_fmamk_f32 v92, v92, 0x3c000000, v156
	v_mul_f32_e32 v93, 0x4b800000, v92
	v_cmp_gt_f32_e32 vcc, s34, v92
	s_nop 1
	v_cndmask_b32_e32 v92, v92, v93, vcc
	v_rsq_f32_e32 v98, v92
	global_load_dwordx4 v[92:95], v144, s[54:55] offset:464
	global_load_dwordx4 v[126:129], v144, s[54:55] offset:448
	v_mul_f32_e32 v51, 0x45800000, v98
	v_cndmask_b32_e32 v51, v98, v51, vcc
	v_mul_f32_e32 v140, 0x3e0293ee, v51
	v_pk_mul_f32 v[98:99], v[140:141], v[132:133] op_sel_hi:[0,1]
	s_waitcnt vmcnt(6)
	v_pk_mul_f32 v[80:81], v[80:81], v[98:99]
	v_pk_mul_f32 v[48:49], v[140:141], v[48:49] op_sel_hi:[0,1]
	v_cvt_pk_bf16_f32 v98, v80, v81
	v_pk_mul_f32 v[80:81], v[140:141], v[130:131] op_sel_hi:[0,1]
	v_pk_mul_f32 v[80:81], v[82:83], v[80:81]
	v_pk_mul_f32 v[14:15], v[48:49], v[14:15]
	v_cvt_pk_bf16_f32 v99, v80, v81
	v_pk_mul_f32 v[80:81], v[140:141], v[100:101] op_sel_hi:[0,1]
	v_pk_mul_f32 v[64:65], v[64:65], v[80:81]
	v_mov_b32_e32 v51, v135
	v_cvt_pk_bf16_f32 v100, v64, v65
	v_pk_mul_f32 v[64:65], v[140:141], v[124:125] op_sel_hi:[0,1]
	v_pk_mul_f32 v[64:65], v[66:67], v[64:65]
	v_mov_b32_e32 v48, v135
	v_cvt_pk_bf16_f32 v101, v64, v65
	v_pk_mul_f32 v[64:65], v[140:141], v[102:103] op_sel_hi:[0,1]
	s_waitcnt vmcnt(4)
	v_pk_mul_f32 v[64:65], v[88:89], v[64:65]
	v_mov_b32_e32 v49, v135
	v_cvt_pk_bf16_f32 v102, v64, v65
	v_pk_mul_f32 v[64:65], v[140:141], v[122:123] op_sel_hi:[0,1]
	v_pk_mul_f32 v[64:65], v[90:91], v[64:65]
	s_nop 0
	v_cvt_pk_bf16_f32 v103, v64, v65
	v_pk_mul_f32 v[64:65], v[140:141], v[104:105] op_sel_hi:[0,1]
	v_pk_mul_f32 v[64:65], v[84:85], v[64:65]
	s_nop 0
	v_cvt_pk_bf16_f32 v104, v64, v65
	v_pk_mul_f32 v[64:65], v[140:141], v[120:121] op_sel_hi:[0,1]
	v_pk_mul_f32 v[64:65], v[86:87], v[64:65]
	s_nop 0
	v_cvt_pk_bf16_f32 v105, v64, v65
	v_pk_mul_f32 v[64:65], v[140:141], v[106:107] op_sel_hi:[0,1]
	v_pk_mul_f32 v[64:65], v[76:77], v[64:65]
	s_nop 0
	v_cvt_pk_bf16_f32 v106, v64, v65
	v_pk_mul_f32 v[64:65], v[140:141], v[118:119] op_sel_hi:[0,1]
	v_pk_mul_f32 v[64:65], v[64:65], v[78:79]
	s_nop 0
	v_cvt_pk_bf16_f32 v107, v64, v65
	v_pk_mul_f32 v[64:65], v[140:141], v[108:109] op_sel_hi:[0,1]
	v_pk_mul_f32 v[64:65], v[64:65], v[68:69]
	s_nop 0
	v_cvt_pk_bf16_f32 v108, v64, v65
	v_pk_mul_f32 v[64:65], v[140:141], v[116:117] op_sel_hi:[0,1]
	v_pk_mul_f32 v[64:65], v[64:65], v[70:71]
	s_nop 0
	v_cvt_pk_bf16_f32 v109, v64, v65
	v_pk_mul_f32 v[64:65], v[140:141], v[110:111] op_sel_hi:[0,1]
	v_pk_mul_f32 v[64:65], v[64:65], v[72:73]
	s_nop 0
	v_cvt_pk_bf16_f32 v110, v64, v65
	v_pk_mul_f32 v[64:65], v[140:141], v[114:115] op_sel_hi:[0,1]
	v_cvt_pk_bf16_f32 v114, v14, v15
	v_pk_mul_f32 v[14:15], v[140:141], v[46:47] op_sel_hi:[0,1]
	v_pk_mul_f32 v[14:15], v[14:15], v[16:17]
	v_pk_mul_f32 v[64:65], v[64:65], v[74:75]
	v_cvt_pk_bf16_f32 v115, v14, v15
	v_pk_mul_f32 v[14:15], v[140:141], v[44:45] op_sel_hi:[0,1]
	v_pk_mul_f32 v[10:11], v[14:15], v[10:11]
	v_add_u32_e32 v15, 0x200, v50
	v_cvt_pk_bf16_f32 v116, v10, v11
	v_pk_mul_f32 v[10:11], v[140:141], v[42:43] op_sel_hi:[0,1]
	v_pk_mul_f32 v[10:11], v[10:11], v[12:13]
	v_cvt_pk_bf16_f32 v111, v64, v65
	v_cvt_pk_bf16_f32 v117, v10, v11
	v_pk_mul_f32 v[10:11], v[140:141], v[40:41] op_sel_hi:[0,1]
	v_pk_mul_f32 v[6:7], v[10:11], v[6:7]
	v_ashrrev_i32_e32 v10, 31, v15
	v_cvt_pk_bf16_f32 v118, v6, v7
	v_pk_mul_f32 v[6:7], v[140:141], v[38:39] op_sel_hi:[0,1]
	v_pk_mul_f32 v[6:7], v[6:7], v[8:9]
	v_lshrrev_b32_e32 v10, 28, v10
	v_cvt_pk_bf16_f32 v119, v6, v7
	v_pk_mul_f32 v[6:7], v[140:141], v[36:37] op_sel_hi:[0,1]
	v_pk_mul_f32 v[2:3], v[6:7], v[2:3]
	v_add_u32_e32 v7, 0x100, v50
	v_cvt_pk_bf16_f32 v120, v2, v3
	v_pk_mul_f32 v[2:3], v[140:141], v[34:35] op_sel_hi:[0,1]
	v_pk_mul_f32 v[2:3], v[2:3], v[4:5]
	v_ashrrev_i32_e32 v6, 31, v7
	v_cvt_pk_bf16_f32 v121, v2, v3
	v_pk_mul_f32 v[2:3], v[140:141], v[32:33] op_sel_hi:[0,1]
	s_waitcnt vmcnt(2)
	v_pk_mul_f32 v[2:3], v[2:3], v[60:61]
	v_lshrrev_b32_e32 v6, 28, v6
	v_cvt_pk_bf16_f32 v122, v2, v3
	v_pk_mul_f32 v[2:3], v[140:141], v[30:31] op_sel_hi:[0,1]
	v_pk_mul_f32 v[2:3], v[2:3], v[62:63]
	v_add_u32_e32 v30, 0x300, v50
	v_cvt_pk_bf16_f32 v123, v2, v3
	v_pk_mul_f32 v[2:3], v[140:141], v[28:29] op_sel_hi:[0,1]
	v_pk_mul_f32 v[2:3], v[2:3], v[56:57]
	v_ashrrev_i32_e32 v14, 31, v30
	v_cvt_pk_bf16_f32 v124, v2, v3
	v_pk_mul_f32 v[2:3], v[140:141], v[26:27] op_sel_hi:[0,1]
	v_pk_mul_f32 v[2:3], v[2:3], v[58:59]
	v_add_u32_e32 v8, v7, v6
	v_cvt_pk_bf16_f32 v125, v2, v3
	v_pk_mul_f32 v[2:3], v[140:141], v[24:25] op_sel_hi:[0,1]
	s_waitcnt vmcnt(0)
	v_pk_mul_f32 v[2:3], v[2:3], v[126:127]
	v_lshrrev_b32_e32 v14, 28, v14
	v_cvt_pk_bf16_f32 v126, v2, v3
	v_pk_mul_f32 v[2:3], v[140:141], v[22:23] op_sel_hi:[0,1]
	v_pk_mul_f32 v[2:3], v[2:3], v[128:129]
	v_ashrrev_i32_e32 v6, 4, v8
	v_cvt_pk_bf16_f32 v127, v2, v3
	v_pk_mul_f32 v[2:3], v[140:141], v[20:21] op_sel_hi:[0,1]
	v_pk_mul_f32 v[2:3], v[2:3], v[92:93]
	v_and_b32_e32 v8, -16, v8
	v_cvt_pk_bf16_f32 v128, v2, v3
	v_pk_mul_f32 v[2:3], v[140:141], v[18:19] op_sel_hi:[0,1]
	v_pk_mul_f32 v[2:3], v[2:3], v[94:95]
	v_add_u32_e32 v12, v15, v10
	v_cvt_pk_bf16_f32 v129, v2, v3
	v_lshlrev_b32_e32 v2, 4, v50
	v_and_b32_e32 v160, 0x70, v2
	v_ashrrev_i32_e32 v2, 31, v50
	v_lshrrev_b32_e32 v2, 28, v2
	v_add_u32_e32 v3, v50, v2
	v_ashrrev_i32_e32 v2, 4, v3
	v_and_b32_e32 v3, -16, v3
	v_add_u32_e32 v16, v30, v14
	v_sub_u32_e32 v3, v50, v3
	v_sub_u32_e32 v11, v7, v8
	v_ashrrev_i32_e32 v10, 4, v12
	v_and_b32_e32 v12, -16, v12
	v_ashrrev_i32_e32 v14, 4, v16
	v_and_b32_e32 v16, -16, v16
	v_pk_mul_f32 v[64:65], v[140:141], v[112:113] op_sel_hi:[0,1]
	v_lshlrev_b32_e32 v4, 3, v3
	v_lshlrev_b32_e32 v8, 3, v11
	v_sub_u32_e32 v34, v15, v12
	v_sub_u32_e32 v35, v30, v16
	v_ashrrev_i32_e32 v18, 3, v50
	v_ashrrev_i32_e32 v22, 3, v7
	v_ashrrev_i32_e32 v26, 3, v15
	v_ashrrev_i32_e32 v30, 3, v30
	v_lshlrev_b32_e32 v162, 4, v3
	v_lshlrev_b32_e32 v164, 4, v11
	v_ashrrev_i32_e32 v15, 31, v14
	v_ashrrev_i32_e32 v11, 31, v10
	v_ashrrev_i32_e32 v7, 31, v6
	v_ashrrev_i32_e32 v3, 31, v2
	v_pk_mul_f32 v[52:53], v[64:65], v[52:53]
	v_ashrrev_i32_e32 v19, 31, v18
	v_ashrrev_i32_e32 v23, 31, v22
	v_ashrrev_i32_e32 v27, 31, v26
	v_ashrrev_i32_e32 v31, 31, v30
	v_mul_lo_u32 v161, v2, s35
	v_mul_lo_u32 v163, v6, s35
	v_mul_lo_u32 v165, v10, s35
	v_mul_lo_u32 v167, v14, s35
	v_lshlrev_b64 v[14:15], 10, v[14:15]
	v_lshlrev_b64 v[10:11], 10, v[10:11]
	v_lshlrev_b64 v[6:7], 10, v[6:7]
	v_lshlrev_b64 v[2:3], 10, v[2:3]
	v_cvt_pk_bf16_f32 v112, v52, v53
	v_pk_mul_f32 v[52:53], v[140:141], v[96:97] op_sel_hi:[0,1]
	v_lshlrev_b32_e32 v12, 3, v34
	v_lshlrev_b32_e32 v16, 3, v35
	v_lshlrev_b64 v[20:21], 9, v[18:19]
	v_lshlrev_b64 v[24:25], 9, v[22:23]
	v_lshlrev_b64 v[28:29], 9, v[26:27]
	v_lshlrev_b64 v[32:33], 9, v[30:31]
	v_lshl_add_u64 v[14:15], s[8:9], 0, v[14:15]
	v_lshl_add_u64 v[10:11], s[8:9], 0, v[10:11]
	v_lshl_add_u64 v[6:7], s[8:9], 0, v[6:7]
	v_lshl_add_u64 v[2:3], s[8:9], 0, v[2:3]
	v_pk_mul_f32 v[52:53], v[52:53], v[54:55]
	v_ashrrev_i32_e32 v5, 31, v4
	v_ashrrev_i32_e32 v9, 31, v8
	v_ashrrev_i32_e32 v13, 31, v12
	v_ashrrev_i32_e32 v17, 31, v16
	v_lshl_add_u64 v[140:141], s[10:11], 0, v[20:21]
	v_lshl_add_u64 v[142:143], s[10:11], 0, v[24:25]
	v_lshl_add_u64 v[144:145], s[10:11], 0, v[28:29]
	v_lshl_add_u64 v[146:147], s[10:11], 0, v[32:33]
	v_or_b32_e32 v14, s41, v14
	v_or_b32_e32 v10, s41, v10
	v_or_b32_e32 v6, s41, v6
	v_or_b32_e32 v2, s41, v2
	v_cvt_pk_bf16_f32 v113, v52, v53
	v_lshlrev_b32_e32 v166, 4, v34
	v_lshlrev_b32_e32 v168, 4, v35
	v_mul_lo_u32 v169, v18, s38
	v_mul_lo_u32 v170, v22, s38
	v_mul_lo_u32 v171, v26, s38
	v_mul_lo_u32 v172, v30, s38
	v_or_b32_e32 v140, v140, v160
	v_or_b32_e32 v142, v142, v160
	v_or_b32_e32 v144, v144, v160
	v_or_b32_e32 v146, v146, v160
	v_lshl_add_u64 v[148:149], v[16:17], 1, v[14:15]
	v_lshl_add_u64 v[150:151], v[12:13], 1, v[10:11]
	v_lshl_add_u64 v[152:153], v[8:9], 1, v[6:7]
	v_lshl_add_u64 v[154:155], v[4:5], 1, v[2:3]
	s_mov_b32 s8, 0
	v_mov_b32_e32 v50, 0
	v_mov_b32_e32 v52, v135
	v_mov_b32_e32 v53, v135
	v_mov_b32_e32 v54, v135
	v_mov_b32_e32 v55, v135
	v_mov_b32_e32 v56, v135
	v_mov_b32_e32 v57, v135
	v_mov_b32_e32 v58, v135
	v_mov_b32_e32 v59, v135
	v_mov_b32_e32 v60, v135
	v_mov_b32_e32 v61, v135
	v_mov_b32_e32 v62, v135
	v_mov_b32_e32 v63, v135
	v_mov_b32_e32 v64, v135
	v_mov_b32_e32 v65, v135
	v_mov_b32_e32 v34, 0
	v_mov_b32_e32 v35, v135
	v_mov_b32_e32 v36, v135
	v_mov_b32_e32 v37, v135
	v_mov_b32_e32 v38, v135
	v_mov_b32_e32 v39, v135
	v_mov_b32_e32 v40, v135
	v_mov_b32_e32 v41, v135
	v_mov_b32_e32 v42, v135
	v_mov_b32_e32 v43, v135
	v_mov_b32_e32 v44, v135
	v_mov_b32_e32 v45, v135
	v_mov_b32_e32 v46, v135
	v_mov_b32_e32 v47, v135
	v_mov_b32_e32 v18, 0
	v_mov_b32_e32 v19, v135
	v_mov_b32_e32 v20, v135
	v_mov_b32_e32 v21, v135
	v_mov_b32_e32 v22, v135
	v_mov_b32_e32 v23, v135
	v_mov_b32_e32 v24, v135
	v_mov_b32_e32 v25, v135
	v_mov_b32_e32 v26, v135
	v_mov_b32_e32 v27, v135
	v_mov_b32_e32 v28, v135
	v_mov_b32_e32 v29, v135
	v_mov_b32_e32 v30, v135
	v_mov_b32_e32 v31, v135
	v_mov_b32_e32 v32, v135
	v_mov_b32_e32 v33, v135
	v_mov_b32_e32 v2, 0
	v_mov_b32_e32 v3, v135
	v_mov_b32_e32 v4, v135
	v_mov_b32_e32 v5, v135
	v_mov_b32_e32 v6, v135
	v_mov_b32_e32 v7, v135
	v_mov_b32_e32 v8, v135
	v_mov_b32_e32 v9, v135
	v_mov_b32_e32 v10, v135
	v_mov_b32_e32 v11, v135
	v_mov_b32_e32 v12, v135
	v_mov_b32_e32 v13, v135
	v_mov_b32_e32 v14, v135
	v_mov_b32_e32 v15, v135
	v_mov_b32_e32 v16, v135
	v_mov_b32_e32 v17, v135
	s_cmp_eq_u32 s98, 1
	s_cbranch_scc1 .Lxf_loop

.Lxa_join:
	ds_bpermute_b32 v66, v139, v178
	v_mov_b32_e32 v139, v135
	s_add_i32 s12, s12, s3
	s_sub_i32 s14, s14, s3
	s_cmpk_gt_i32 s12, 0x3ff
	s_waitcnt lgkmcnt(0)
	v_add_f32_e32 v68, v178, v66
	v_div_scale_f32 v69, s[8:9], v68, v68, 1.0
	v_rcp_f32_e32 v70, v69
	v_div_scale_f32 v71, vcc, 1.0, v68, 1.0
	v_lshl_add_u64 v[66:67], v[136:137], 0, v[138:139]
	v_fma_f32 v72, -v69, v70, 1.0
	v_fmac_f32_e32 v70, v72, v70
	v_mul_f32_e32 v72, v71, v70
	v_fma_f32 v73, -v69, v72, v71
	v_fmac_f32_e32 v72, v73, v70
	v_fma_f32 v69, -v69, v72, v71
	v_div_fmas_f32 v69, v69, v70, v72
	v_div_fixup_f32 v68, v69, v68, 1.0
	v_pk_mul_f32 v[50:51], v[50:51], v[68:69] op_sel_hi:[1,0]
	v_pk_mul_f32 v[52:53], v[52:53], v[68:69] op_sel_hi:[1,0]
	v_pk_mul_f32 v[34:35], v[34:35], v[68:69] op_sel_hi:[1,0]
	v_pk_mul_f32 v[36:37], v[36:37], v[68:69] op_sel_hi:[1,0]
	v_pk_mul_f32 v[18:19], v[18:19], v[68:69] op_sel_hi:[1,0]
	v_pk_mul_f32 v[20:21], v[20:21], v[68:69] op_sel_hi:[1,0]
	v_pk_mul_f32 v[2:3], v[2:3], v[68:69] op_sel_hi:[1,0]
	v_pk_mul_f32 v[4:5], v[4:5], v[68:69] op_sel_hi:[1,0]
	v_cvt_pk_bf16_f32 v50, v50, v51
	v_cvt_pk_bf16_f32 v51, v52, v53
	v_cvt_pk_bf16_f32 v34, v34, v35
	v_cvt_pk_bf16_f32 v35, v36, v37
	v_cvt_pk_bf16_f32 v18, v18, v19
	v_cvt_pk_bf16_f32 v19, v20, v21
	v_cvt_pk_bf16_f32 v2, v2, v3
	v_cvt_pk_bf16_f32 v3, v4, v5
	global_store_dwordx2 v[66:67], v[50:51], off
	v_pk_mul_f32 v[50:51], v[54:55], v[68:69] op_sel_hi:[1,0]
	v_pk_mul_f32 v[52:53], v[56:57], v[68:69] op_sel_hi:[1,0]
	global_store_dwordx2 v[66:67], v[34:35], off offset:64
	v_pk_mul_f32 v[34:35], v[38:39], v[68:69] op_sel_hi:[1,0]
	v_pk_mul_f32 v[36:37], v[40:41], v[68:69] op_sel_hi:[1,0]
	global_store_dwordx2 v[66:67], v[18:19], off offset:128
	v_pk_mul_f32 v[18:19], v[22:23], v[68:69] op_sel_hi:[1,0]
	v_pk_mul_f32 v[20:21], v[24:25], v[68:69] op_sel_hi:[1,0]
	global_store_dwordx2 v[66:67], v[2:3], off offset:192
	v_pk_mul_f32 v[2:3], v[6:7], v[68:69] op_sel_hi:[1,0]
	v_pk_mul_f32 v[4:5], v[8:9], v[68:69] op_sel_hi:[1,0]
	v_cvt_pk_bf16_f32 v50, v50, v51
	v_cvt_pk_bf16_f32 v51, v52, v53
	v_cvt_pk_bf16_f32 v34, v34, v35
	v_cvt_pk_bf16_f32 v35, v36, v37
	v_cvt_pk_bf16_f32 v18, v18, v19
	v_cvt_pk_bf16_f32 v19, v20, v21
	v_cvt_pk_bf16_f32 v2, v2, v3
	v_cvt_pk_bf16_f32 v3, v4, v5
	global_store_dwordx2 v[66:67], v[50:51], off offset:16
	v_pk_mul_f32 v[50:51], v[58:59], v[68:69] op_sel_hi:[1,0]
	v_pk_mul_f32 v[52:53], v[60:61], v[68:69] op_sel_hi:[1,0]
	global_store_dwordx2 v[66:67], v[34:35], off offset:80
	v_pk_mul_f32 v[34:35], v[42:43], v[68:69] op_sel_hi:[1,0]
	v_pk_mul_f32 v[36:37], v[44:45], v[68:69] op_sel_hi:[1,0]
	global_store_dwordx2 v[66:67], v[18:19], off offset:144
	v_pk_mul_f32 v[18:19], v[26:27], v[68:69] op_sel_hi:[1,0]
	v_pk_mul_f32 v[20:21], v[28:29], v[68:69] op_sel_hi:[1,0]
	global_store_dwordx2 v[66:67], v[2:3], off offset:208
	v_pk_mul_f32 v[2:3], v[10:11], v[68:69] op_sel_hi:[1,0]
	v_pk_mul_f32 v[4:5], v[12:13], v[68:69] op_sel_hi:[1,0]
	v_cvt_pk_bf16_f32 v50, v50, v51
	v_cvt_pk_bf16_f32 v51, v52, v53
	v_cvt_pk_bf16_f32 v34, v34, v35
	v_cvt_pk_bf16_f32 v35, v36, v37
	v_cvt_pk_bf16_f32 v18, v18, v19
	v_cvt_pk_bf16_f32 v19, v20, v21
	v_cvt_pk_bf16_f32 v2, v2, v3
	v_cvt_pk_bf16_f32 v3, v4, v5
	global_store_dwordx2 v[66:67], v[50:51], off offset:32
	v_pk_mul_f32 v[50:51], v[62:63], v[68:69] op_sel_hi:[1,0]
	v_pk_mul_f32 v[52:53], v[64:65], v[68:69] op_sel_hi:[1,0]
	global_store_dwordx2 v[66:67], v[34:35], off offset:96
	v_pk_mul_f32 v[34:35], v[46:47], v[68:69] op_sel_hi:[1,0]
	v_pk_mul_f32 v[36:37], v[48:49], v[68:69] op_sel_hi:[1,0]
	global_store_dwordx2 v[66:67], v[18:19], off offset:160
	v_pk_mul_f32 v[18:19], v[30:31], v[68:69] op_sel_hi:[1,0]
	v_pk_mul_f32 v[20:21], v[32:33], v[68:69] op_sel_hi:[1,0]
	global_store_dwordx2 v[66:67], v[2:3], off offset:224
	v_pk_mul_f32 v[2:3], v[14:15], v[68:69] op_sel_hi:[1,0]
	v_pk_mul_f32 v[4:5], v[16:17], v[68:69] op_sel_hi:[1,0]
	v_cvt_pk_bf16_f32 v50, v50, v51
	v_cvt_pk_bf16_f32 v51, v52, v53
	v_cvt_pk_bf16_f32 v34, v34, v35
	v_cvt_pk_bf16_f32 v35, v36, v37
	v_cvt_pk_bf16_f32 v18, v18, v19
	v_cvt_pk_bf16_f32 v19, v20, v21
	v_cvt_pk_bf16_f32 v2, v2, v3
	v_cvt_pk_bf16_f32 v3, v4, v5
	global_store_dwordx2 v[66:67], v[50:51], off offset:48
	global_store_dwordx2 v[66:67], v[34:35], off offset:112
	global_store_dwordx2 v[66:67], v[18:19], off offset:176
	global_store_dwordx2 v[66:67], v[2:3], off offset:240
	s_cbranch_scc0 .LBB0_830
